# LayerNorm adaLN shift/scale quads loaded once per 4-row iteration (hoisted ahead of the LN math) instead of 8 serialized load+vmcnt(0) pairs per row
# speedup vs baseline: 1.0523x; 1.0088x over previous
.LBB0_110:
	v_lshrrev_b32_e32 v7, 20, v7
	v_add_u32_e32 v7, v98, v7
	v_ashrrev_i32_e32 v7, 12, v7
	v_add_u32_e32 v7, s2, v7
	v_mul_hi_i32_i24_e32 v39, 0x3000, v7
	v_mul_i32_i24_e32 v38, 0x3000, v7
	v_lshl_add_u64 v[40:41], s[84:85], 0, v[38:39]
	v_lshl_add_u64 v[38:39], v[40:41], 0, s[8:9]
	v_lshl_add_u64 v[40:41], v[40:41], 0, v[94:95]
	v_lshl_add_u64 v[46:47], v[38:39], 0, v[94:95]
	v_add_f32_e32 v15, v32, v33
	v_add_f32_e32 v19, v34, v35
	v_add_f32_e32 v15, v15, v19
	v_add_f32_e32 v19, v28, v29
	v_add_f32_e32 v36, v30, v31
	v_add_f32_e32 v15, 0, v15
	v_add_f32_e32 v19, v19, v36
	v_add_f32_e32 v15, v19, v15
	v_add_f32_e32 v19, v24, v25
	v_add_f32_e32 v36, v26, v27
	v_add_f32_e32 v19, v19, v36
	v_add_f32_e32 v15, v19, v15
	v_add_f32_e32 v19, v20, v21
	v_add_f32_e32 v36, v22, v23
	v_add_f32_e32 v19, v19, v36
	v_add_f32_e32 v15, v19, v15
	s_add_i32 s3, s3, s26
	v_add_u32_e32 v86, s75, v86
	v_add_f32_dpp v15, v15, v15 row_ror:8 row_mask:0xf bank_mask:0xf bound_ctrl:1
	s_cmpk_lt_i32 s3, 0x400
	s_nop 0
	v_mov_b64_e32 v[42:43], v[138:139]
	v_mov_b64_e32 v[44:45], v[140:141]
	v_mov_b64_e32 v[46:47], v[154:155]
	v_mov_b64_e32 v[48:49], v[156:157]
	v_pk_add_f32 v[48:49], v[48:49], 1.0 op_sel_hi:[1,0]
	v_add_f32_dpp v15, v15, v15 row_ror:4 row_mask:0xf bank_mask:0xf bound_ctrl:1
	v_pk_add_f32 v[46:47], v[46:47], 1.0 op_sel_hi:[1,0]
	s_nop 0
	v_add_f32_dpp v15, v15, v15 row_ror:2 row_mask:0xf bank_mask:0xf bound_ctrl:1
	s_nop 1
	v_add_f32_dpp v15, v15, v15 row_ror:1 row_mask:0xf bank_mask:0xf bound_ctrl:1
	v_mov_b32_e32 v19, v15
	s_nop 1
	v_permlane16_swap_b32_e32 v15, v19
	v_add_f32_e32 v15, v15, v19
	v_mov_b32_e32 v19, v15
	s_nop 1
	v_permlane32_swap_b32_e32 v15, v19
	v_add_f32_e32 v15, v15, v19
	v_fmamk_f32 v37, v15, 0xba800000, v35
	v_fmac_f32_e32 v33, 0xba800000, v15
	v_fmamk_f32 v36, v15, 0xba800000, v34
	v_fmamk_f32 v32, v15, 0xba800000, v32
	v_mul_f32_e32 v19, v33, v33
	v_mul_f32_e32 v34, v37, v37
	v_fmac_f32_e32 v19, v32, v32
	v_fmac_f32_e32 v34, v36, v36
	v_fmamk_f32 v35, v15, 0xba800000, v31
	v_fmac_f32_e32 v29, 0xba800000, v15
	v_add_f32_e32 v19, v19, v34
	v_fmamk_f32 v34, v15, 0xba800000, v30
	v_fmamk_f32 v28, v15, 0xba800000, v28
	v_mul_f32_e32 v30, v29, v29
	v_mul_f32_e32 v31, v35, v35
	v_fmac_f32_e32 v30, v28, v28
	v_fmac_f32_e32 v31, v34, v34
	v_add_f32_e32 v30, v30, v31
	v_fmamk_f32 v31, v15, 0xba800000, v27
	v_fmac_f32_e32 v25, 0xba800000, v15
	v_add_f32_e32 v19, v19, v30
	v_fmamk_f32 v30, v15, 0xba800000, v26
	v_fmamk_f32 v24, v15, 0xba800000, v24
	v_mul_f32_e32 v26, v25, v25
	v_mul_f32_e32 v27, v31, v31
	v_fmac_f32_e32 v26, v24, v24
	v_fmac_f32_e32 v27, v30, v30
	v_add_f32_e32 v26, v26, v27
	v_fmamk_f32 v23, v15, 0xba800000, v23
	v_fmac_f32_e32 v21, 0xba800000, v15
	v_add_f32_e32 v19, v26, v19
	v_fmamk_f32 v22, v15, 0xba800000, v22
	v_fmamk_f32 v20, v15, 0xba800000, v20
	v_mul_f32_e32 v15, v21, v21
	v_mul_f32_e32 v26, v23, v23
	v_fmac_f32_e32 v15, v20, v20
	v_fmac_f32_e32 v26, v22, v22
	v_add_f32_e32 v15, v15, v26
	v_add_f32_e32 v15, v15, v19
	s_nop 1
	v_add_f32_dpp v15, v15, v15 row_ror:8 row_mask:0xf bank_mask:0xf bound_ctrl:1
	s_nop 1
	v_add_f32_dpp v15, v15, v15 row_ror:4 row_mask:0xf bank_mask:0xf bound_ctrl:1
	s_nop 1
	v_add_f32_dpp v15, v15, v15 row_ror:2 row_mask:0xf bank_mask:0xf bound_ctrl:1
	s_nop 1
	v_add_f32_dpp v15, v15, v15 row_ror:1 row_mask:0xf bank_mask:0xf bound_ctrl:1
	v_mov_b32_e32 v19, v15
	s_nop 1
	v_permlane16_swap_b32_e32 v15, v19
	v_add_f32_e32 v15, v15, v19
	v_mov_b32_e32 v19, v15
	s_nop 1
	v_permlane32_swap_b32_e32 v15, v19
	v_add_f32_e32 v15, v15, v19
	v_fmamk_f32 v15, v15, 0x3a800000, v196
	v_cmp_gt_f32_e32 vcc, s22, v15
	v_mul_f32_e32 v19, 0x4b800000, v15
	s_nop 0
	v_cndmask_b32_e32 v15, v15, v19, vcc
	v_rsq_f32_e32 v15, v15
	s_nop 0
	v_mul_f32_e32 v19, 0x45800000, v15
	v_cndmask_b32_e32 v26, v15, v19, vcc
	v_pk_mul_f32 v[32:33], v[32:33], v[26:27] op_sel_hi:[1,0]
	v_pk_mul_f32 v[36:37], v[36:37], v[26:27] op_sel_hi:[1,0]
	v_pk_fma_f32 v[32:33], v[46:47], v[32:33], v[42:43]
	v_pk_fma_f32 v[36:37], v[48:49], v[36:37], v[44:45]
	v_cvt_pk_bf16_f32 v32, v32, v33
	v_cvt_pk_bf16_f32 v33, v36, v37
	v_lshl_add_u64 v[36:37], v[84:85], 0, v[96:97]
	global_store_dwordx2 v[36:37], v[32:33], off
	v_lshl_add_u64 v[32:33], v[38:39], 0, v[88:89]
	v_pk_mul_f32 v[28:29], v[28:29], v[26:27] op_sel_hi:[1,0]
	v_pk_mul_f32 v[32:33], v[34:35], v[26:27] op_sel_hi:[1,0]
	v_pk_mul_f32 v[24:25], v[24:25], v[26:27] op_sel_hi:[1,0]
	v_pk_mul_f32 v[20:21], v[20:21], v[26:27] op_sel_hi:[1,0]
	v_pk_mul_f32 v[22:23], v[22:23], v[26:27] op_sel_hi:[1,0]
	s_nop 0
	v_mov_b64_e32 v[42:43], v[142:143]
	v_mov_b64_e32 v[44:45], v[144:145]
	v_mov_b64_e32 v[46:47], v[158:159]
	v_mov_b64_e32 v[48:49], v[160:161]
	v_pk_add_f32 v[34:35], v[48:49], 1.0 op_sel_hi:[1,0]
	v_pk_add_f32 v[46:47], v[46:47], 1.0 op_sel_hi:[1,0]
	v_pk_fma_f32 v[32:33], v[34:35], v[32:33], v[44:45]
	v_pk_fma_f32 v[28:29], v[46:47], v[28:29], v[42:43]
	s_nop 0
	v_cvt_pk_bf16_f32 v28, v28, v29
	v_cvt_pk_bf16_f32 v29, v32, v33
	global_store_dwordx2 v[36:37], v[28:29], off offset:512
	v_lshl_add_u64 v[28:29], v[38:39], 0, v[90:91]
	v_pk_mul_f32 v[28:29], v[30:31], v[26:27] op_sel_hi:[1,0]
	s_nop 0
	v_mov_b64_e32 v[32:33], v[146:147]
	v_mov_b64_e32 v[34:35], v[148:149]
	v_mov_b64_e32 v[42:43], v[162:163]
	v_mov_b64_e32 v[44:45], v[164:165]
	v_pk_add_f32 v[30:31], v[44:45], 1.0 op_sel_hi:[1,0]
	v_pk_add_f32 v[42:43], v[42:43], 1.0 op_sel_hi:[1,0]
	v_pk_fma_f32 v[28:29], v[30:31], v[28:29], v[34:35]
	v_pk_fma_f32 v[24:25], v[42:43], v[24:25], v[32:33]
	s_nop 0
	v_cvt_pk_bf16_f32 v24, v24, v25
	v_cvt_pk_bf16_f32 v25, v28, v29
	global_store_dwordx2 v[36:37], v[24:25], off offset:1024
	v_lshl_add_u64 v[24:25], v[38:39], 0, v[92:93]
	s_nop 0
	v_mov_b64_e32 v[28:29], v[150:151]
	v_mov_b64_e32 v[30:31], v[152:153]
	v_mov_b64_e32 v[32:33], v[166:167]
	v_mov_b64_e32 v[34:35], v[168:169]
	v_pk_add_f32 v[24:25], v[34:35], 1.0 op_sel_hi:[1,0]
	v_pk_add_f32 v[26:27], v[32:33], 1.0 op_sel_hi:[1,0]
	v_pk_fma_f32 v[22:23], v[24:25], v[22:23], v[30:31]
	v_pk_fma_f32 v[20:21], v[26:27], v[20:21], v[28:29]
	s_nop 0
	v_cvt_pk_bf16_f32 v20, v20, v21
	v_cvt_pk_bf16_f32 v21, v22, v23
	global_store_dwordx2 v[36:37], v[20:21], off offset:1536
	s_cbranch_scc0 .LBB0_127

.LBB0_119:
	v_ashrrev_i32_e32 v186, 12, v86
	v_add_u32_e32 v186, s2, v186
	v_mul_hi_i32_i24_e32 v189, 0x3000, v186
	v_mul_i32_i24_e32 v188, 0x3000, v186
	v_lshl_add_u64 v[188:189], s[84:85], 0, v[188:189]
	v_lshl_add_u64 v[188:189], v[188:189], 0, v[94:95]
	s_mov_b64 s[100:101], 0x1000
	v_lshl_add_u64 v[186:187], v[188:189], 0, s[100:101]
	global_load_dwordx4 v[138:141], v[188:189], off
	global_load_dwordx4 v[142:145], v[188:189], off offset:1024
	global_load_dwordx4 v[146:149], v[188:189], off offset:2048
	global_load_dwordx4 v[150:153], v[188:189], off offset:3072
	global_load_dwordx4 v[154:157], v[186:187], off
	global_load_dwordx4 v[158:161], v[186:187], off offset:1024
	global_load_dwordx4 v[162:165], v[186:187], off offset:2048
	global_load_dwordx4 v[166:169], v[186:187], off offset:3072
	s_and_b64 vcc, exec, s[38:39]
	s_cbranch_vccnz .LBB0_121
	global_load_dwordx4 v[120:123], v[8:9], off
	global_load_dwordx4 v[124:127], v[12:13], off
	s_waitcnt vmcnt(17)
	v_add_f32_e32 v89, v80, v81
	v_add_f32_e32 v91, v82, v83
	v_add_f32_e32 v89, v89, v91
	s_waitcnt vmcnt(16)
	v_add_f32_e32 v91, v76, v77
	v_add_f32_e32 v93, v78, v79
	v_add_f32_e32 v89, 0, v89
	v_add_f32_e32 v91, v91, v93
	v_add_f32_e32 v89, v91, v89
	s_waitcnt vmcnt(15)
	v_add_f32_e32 v91, v72, v73
	v_add_f32_e32 v93, v74, v75
	v_add_f32_e32 v91, v91, v93
	v_add_f32_e32 v89, v91, v89
	s_waitcnt vmcnt(14)
	v_add_f32_e32 v91, v68, v69
	v_add_f32_e32 v93, v70, v71
	v_add_f32_e32 v91, v91, v93
	v_add_f32_e32 v89, v91, v89
	v_lshl_add_u64 v[116:117], v[16:17], 0, v[116:117]
	s_nop 0
	v_add_f32_dpp v89, v89, v89 row_ror:8 row_mask:0xf bank_mask:0xf bound_ctrl:1
	s_nop 1
	v_add_f32_dpp v89, v89, v89 row_ror:4 row_mask:0xf bank_mask:0xf bound_ctrl:1
	s_nop 1
	v_add_f32_dpp v89, v89, v89 row_ror:2 row_mask:0xf bank_mask:0xf bound_ctrl:1
	s_nop 1
	v_add_f32_dpp v89, v89, v89 row_ror:1 row_mask:0xf bank_mask:0xf bound_ctrl:1
	v_mov_b32_e32 v91, v89
	s_nop 1
	v_permlane16_swap_b32_e32 v89, v91
	v_add_f32_e32 v89, v89, v91
	v_mov_b32_e32 v91, v89
	s_nop 1
	v_permlane32_swap_b32_e32 v89, v91
	v_add_f32_e32 v89, v89, v91
	v_fmamk_f32 v83, v89, 0xba800000, v83
	v_fmac_f32_e32 v81, 0xba800000, v89
	v_fmamk_f32 v82, v89, 0xba800000, v82
	v_fmamk_f32 v80, v89, 0xba800000, v80
	v_mul_f32_e32 v91, v81, v81
	v_mul_f32_e32 v93, v83, v83
	v_fmac_f32_e32 v91, v80, v80
	v_fmac_f32_e32 v93, v82, v82
	v_fmamk_f32 v79, v89, 0xba800000, v79
	v_fmac_f32_e32 v77, 0xba800000, v89
	v_add_f32_e32 v91, v91, v93
	v_fmamk_f32 v78, v89, 0xba800000, v78
	v_fmamk_f32 v76, v89, 0xba800000, v76
	v_mul_f32_e32 v93, v77, v77
	v_mul_f32_e32 v95, v79, v79
	v_fmac_f32_e32 v93, v76, v76
	v_fmac_f32_e32 v95, v78, v78
	v_add_f32_e32 v93, v93, v95
	v_fmamk_f32 v75, v89, 0xba800000, v75
	v_fmac_f32_e32 v73, 0xba800000, v89
	v_add_f32_e32 v91, v91, v93
	v_fmamk_f32 v74, v89, 0xba800000, v74
	v_fmamk_f32 v72, v89, 0xba800000, v72
	v_mul_f32_e32 v93, v73, v73
	v_mul_f32_e32 v95, v75, v75
	v_fmac_f32_e32 v93, v72, v72
	v_fmac_f32_e32 v95, v74, v74
	v_add_f32_e32 v93, v93, v95
	v_fmamk_f32 v71, v89, 0xba800000, v71
	v_fmac_f32_e32 v69, 0xba800000, v89
	v_add_f32_e32 v91, v93, v91
	v_fmamk_f32 v70, v89, 0xba800000, v70
	v_fmamk_f32 v68, v89, 0xba800000, v68
	v_mul_f32_e32 v89, v69, v69
	v_mul_f32_e32 v93, v71, v71
	v_fmac_f32_e32 v89, v68, v68
	v_fmac_f32_e32 v93, v70, v70
	v_add_f32_e32 v89, v89, v93
	v_add_f32_e32 v89, v89, v91
	s_nop 1
	v_add_f32_dpp v89, v89, v89 row_ror:8 row_mask:0xf bank_mask:0xf bound_ctrl:1
	s_nop 1
	v_add_f32_dpp v89, v89, v89 row_ror:4 row_mask:0xf bank_mask:0xf bound_ctrl:1
	s_nop 1
	v_add_f32_dpp v89, v89, v89 row_ror:2 row_mask:0xf bank_mask:0xf bound_ctrl:1
	s_nop 1
	v_add_f32_dpp v89, v89, v89 row_ror:1 row_mask:0xf bank_mask:0xf bound_ctrl:1
	v_mov_b32_e32 v91, v89
	s_nop 1
	v_permlane16_swap_b32_e32 v89, v91
	v_add_f32_e32 v89, v89, v91
	v_mov_b32_e32 v91, v89
	s_nop 1
	v_permlane32_swap_b32_e32 v89, v91
	v_add_f32_e32 v89, v89, v91
	v_fmamk_f32 v89, v89, 0x3a800000, v196
	v_cmp_gt_f32_e32 vcc, s22, v89
	v_mul_f32_e32 v91, 0x4b800000, v89
	s_nop 0
	v_cndmask_b32_e32 v89, v89, v91, vcc
	v_rsq_f32_e32 v89, v89
	s_nop 0
	v_mul_f32_e32 v91, 0x45800000, v89
	v_cndmask_b32_e32 v118, v89, v91, vcc
	v_pk_mul_f32 v[80:81], v[80:81], v[118:119] op_sel_hi:[1,0]
	v_pk_mul_f32 v[82:83], v[82:83], v[118:119] op_sel_hi:[1,0]
	s_waitcnt vmcnt(0)
	v_pk_fma_f32 v[80:81], v[120:121], v[80:81], v[124:125]
	v_pk_fma_f32 v[82:83], v[122:123], v[82:83], v[126:127]
	global_store_dwordx4 v[116:117], v[80:83], off nt
	global_load_dwordx4 v[120:123], v[8:9], off offset:1024
	global_load_dwordx4 v[124:127], v[12:13], off offset:1024
	v_pk_mul_f32 v[78:79], v[78:79], v[118:119] op_sel_hi:[1,0]
	v_pk_mul_f32 v[76:77], v[76:77], v[118:119] op_sel_hi:[1,0]
	v_pk_mul_f32 v[74:75], v[74:75], v[118:119] op_sel_hi:[1,0]
	v_pk_mul_f32 v[72:73], v[72:73], v[118:119] op_sel_hi:[1,0]
	v_pk_mul_f32 v[70:71], v[70:71], v[118:119] op_sel_hi:[1,0]
	v_pk_mul_f32 v[68:69], v[68:69], v[118:119] op_sel_hi:[1,0]
	s_waitcnt vmcnt(0)
	v_pk_fma_f32 v[76:77], v[120:121], v[76:77], v[124:125]
	v_pk_fma_f32 v[78:79], v[122:123], v[78:79], v[126:127]
	global_store_dwordx4 v[116:117], v[76:79], off offset:1024 nt
	global_load_dwordx4 v[120:123], v[8:9], off offset:2048
	global_load_dwordx4 v[124:127], v[12:13], off offset:2048
	s_waitcnt vmcnt(0)
	v_pk_fma_f32 v[72:73], v[120:121], v[72:73], v[124:125]
	v_pk_fma_f32 v[74:75], v[122:123], v[74:75], v[126:127]
	global_store_dwordx4 v[116:117], v[72:75], off offset:2048 nt
	global_load_dwordx4 v[120:123], v[8:9], off offset:3072
	global_load_dwordx4 v[124:127], v[12:13], off offset:3072
	s_waitcnt vmcnt(0)
	v_pk_fma_f32 v[68:69], v[120:121], v[68:69], v[124:125]
	v_pk_fma_f32 v[70:71], v[122:123], v[70:71], v[126:127]
	global_store_dwordx4 v[116:117], v[68:71], off offset:3072 nt
.LBB0_121:
	s_waitcnt vmcnt(15)
	v_add_f32_e32 v89, v80, v81
	v_add_f32_e32 v91, v82, v83
	v_add_f32_e32 v89, v89, v91
	s_waitcnt vmcnt(14)
	v_add_f32_e32 v91, v76, v77
	v_add_f32_e32 v93, v78, v79
	v_add_f32_e32 v89, 0, v89
	v_add_f32_e32 v91, v91, v93
	v_add_f32_e32 v89, v91, v89
	s_waitcnt vmcnt(13)
	v_add_f32_e32 v91, v72, v73
	v_add_f32_e32 v93, v74, v75
	v_add_f32_e32 v91, v91, v93
	v_add_f32_e32 v89, v91, v89
	s_waitcnt vmcnt(12)
	v_add_f32_e32 v91, v68, v69
	v_add_f32_e32 v93, v70, v71
	v_add_f32_e32 v91, v91, v93
	v_add_f32_e32 v89, v91, v89
	v_lshrrev_b32_e32 v87, 20, v87
	v_add_u32_e32 v87, v86, v87
	v_add_f32_dpp v89, v89, v89 row_ror:8 row_mask:0xf bank_mask:0xf bound_ctrl:1
	v_ashrrev_i32_e32 v87, 12, v87
	s_mov_b64 s[8:9], 0x1000
	v_add_f32_dpp v89, v89, v89 row_ror:4 row_mask:0xf bank_mask:0xf bound_ctrl:1
	v_mov_b32_e32 v95, v2
	v_mov_b32_e32 v93, v2
	v_add_f32_dpp v89, v89, v89 row_ror:2 row_mask:0xf bank_mask:0xf bound_ctrl:1
	s_nop 1
	v_add_f32_dpp v89, v89, v89 row_ror:1 row_mask:0xf bank_mask:0xf bound_ctrl:1
	v_mov_b32_e32 v91, v89
	s_nop 1
	v_permlane16_swap_b32_e32 v89, v91
	v_add_f32_e32 v89, v89, v91
	v_mov_b32_e32 v91, v89
	s_nop 1
	v_permlane32_swap_b32_e32 v89, v91
	v_add_f32_e32 v89, v89, v91
	v_fmamk_f32 v117, v89, 0xba800000, v83
	v_fmac_f32_e32 v81, 0xba800000, v89
	v_fmamk_f32 v116, v89, 0xba800000, v82
	v_fmamk_f32 v80, v89, 0xba800000, v80
	v_mul_f32_e32 v82, v81, v81
	v_mul_f32_e32 v83, v117, v117
	v_fmac_f32_e32 v82, v80, v80
	v_fmac_f32_e32 v83, v116, v116
	v_add_f32_e32 v91, v82, v83
	v_fmamk_f32 v83, v89, 0xba800000, v79
	v_fmac_f32_e32 v77, 0xba800000, v89
	v_fmamk_f32 v82, v89, 0xba800000, v78
	v_fmamk_f32 v76, v89, 0xba800000, v76
	v_mul_f32_e32 v78, v77, v77
	v_mul_f32_e32 v79, v83, v83
	v_fmac_f32_e32 v78, v76, v76
	v_fmac_f32_e32 v79, v82, v82
	v_add_f32_e32 v78, v78, v79
	v_fmamk_f32 v79, v89, 0xba800000, v75
	v_fmac_f32_e32 v73, 0xba800000, v89
	v_add_f32_e32 v91, v91, v78
	v_fmamk_f32 v78, v89, 0xba800000, v74
	v_fmamk_f32 v72, v89, 0xba800000, v72
	v_mul_f32_e32 v74, v73, v73
	v_mul_f32_e32 v75, v79, v79
	v_fmac_f32_e32 v74, v72, v72
	v_fmac_f32_e32 v75, v78, v78
	v_fmamk_f32 v71, v89, 0xba800000, v71
	v_fmac_f32_e32 v69, 0xba800000, v89
	v_add_f32_e32 v74, v74, v75
	v_fmamk_f32 v70, v89, 0xba800000, v70
	v_fmamk_f32 v68, v89, 0xba800000, v68
	v_mul_f32_e32 v75, v69, v69
	v_mul_f32_e32 v89, v71, v71
	v_fmac_f32_e32 v75, v68, v68
	v_fmac_f32_e32 v89, v70, v70
	v_add_f32_e32 v74, v74, v91
	v_add_f32_e32 v75, v75, v89
	v_add_f32_e32 v74, v75, v74
	v_mov_b32_e32 v89, v2
	v_mov_b32_e32 v91, v2
	v_add_f32_dpp v74, v74, v74 row_ror:8 row_mask:0xf bank_mask:0xf bound_ctrl:1
	s_nop 1
	v_add_f32_dpp v74, v74, v74 row_ror:4 row_mask:0xf bank_mask:0xf bound_ctrl:1
	s_nop 1
	v_add_f32_dpp v74, v74, v74 row_ror:2 row_mask:0xf bank_mask:0xf bound_ctrl:1
	s_nop 1
	v_add_f32_dpp v74, v74, v74 row_ror:1 row_mask:0xf bank_mask:0xf bound_ctrl:1
	v_mov_b32_e32 v75, v74
	s_nop 1
	v_permlane16_swap_b32_e32 v74, v75
	v_add_f32_e32 v74, v74, v75
	v_mov_b32_e32 v75, v74
	s_nop 1
	v_permlane32_swap_b32_e32 v74, v75
	v_add_f32_e32 v74, v74, v75
	v_fmamk_f32 v74, v74, 0x3a800000, v196
	v_cmp_gt_f32_e32 vcc, s22, v74
	v_mul_f32_e32 v75, 0x4b800000, v74
	s_nop 0
	v_cndmask_b32_e32 v74, v74, v75, vcc
	v_rsq_f32_e32 v74, v74
	s_nop 0
	v_mul_f32_e32 v75, 0x45800000, v74
	v_cndmask_b32_e32 v74, v74, v75, vcc
	v_add_u32_e32 v75, s2, v87
	v_mul_hi_i32_i24_e32 v119, 0x3000, v75
	v_mul_i32_i24_e32 v118, 0x3000, v75
	v_lshl_add_u64 v[120:121], s[84:85], 0, v[118:119]
	v_lshl_add_u64 v[118:119], v[120:121], 0, s[8:9]
	v_lshl_add_u64 v[120:121], v[120:121], 0, v[94:95]
	v_lshl_add_u64 v[126:127], v[118:119], 0, v[94:95]
	v_pk_mul_f32 v[80:81], v[80:81], v[74:75] op_sel_hi:[1,0]
	v_pk_mul_f32 v[116:117], v[116:117], v[74:75] op_sel_hi:[1,0]
	v_pk_mul_f32 v[76:77], v[76:77], v[74:75] op_sel_hi:[1,0]
	v_pk_mul_f32 v[72:73], v[72:73], v[74:75] op_sel_hi:[1,0]
	v_pk_mul_f32 v[68:69], v[68:69], v[74:75] op_sel_hi:[1,0]
	v_pk_mul_f32 v[70:71], v[70:71], v[74:75] op_sel_hi:[1,0]
	s_and_b64 vcc, exec, s[38:39]
	s_waitcnt vmcnt(0)
	v_mov_b64_e32 v[122:123], v[138:139]
	v_mov_b64_e32 v[124:125], v[140:141]
	v_mov_b64_e32 v[126:127], v[154:155]
	v_mov_b64_e32 v[128:129], v[156:157]
	v_pk_add_f32 v[128:129], v[128:129], 1.0 op_sel_hi:[1,0]
	v_pk_add_f32 v[126:127], v[126:127], 1.0 op_sel_hi:[1,0]
	v_pk_fma_f32 v[116:117], v[128:129], v[116:117], v[124:125]
	v_pk_fma_f32 v[80:81], v[126:127], v[80:81], v[122:123]
	v_lshl_add_u64 v[126:127], v[84:85], 0, v[114:115]
	v_cvt_pk_bf16_f32 v80, v80, v81
	v_cvt_pk_bf16_f32 v81, v116, v117
	global_store_dwordx2 v[126:127], v[80:81], off
	v_lshl_add_u64 v[80:81], v[118:119], 0, v[88:89]
	v_pk_mul_f32 v[80:81], v[82:83], v[74:75] op_sel_hi:[1,0]
	s_nop 0
	v_mov_b64_e32 v[114:115], v[142:143]
	v_mov_b64_e32 v[116:117], v[144:145]
	v_mov_b64_e32 v[122:123], v[158:159]
	v_mov_b64_e32 v[124:125], v[160:161]
	v_pk_add_f32 v[82:83], v[124:125], 1.0 op_sel_hi:[1,0]
	v_pk_add_f32 v[122:123], v[122:123], 1.0 op_sel_hi:[1,0]
	v_pk_fma_f32 v[80:81], v[82:83], v[80:81], v[116:117]
	v_pk_fma_f32 v[76:77], v[122:123], v[76:77], v[114:115]
	s_nop 0
	v_cvt_pk_bf16_f32 v76, v76, v77
	v_cvt_pk_bf16_f32 v77, v80, v81
	global_store_dwordx2 v[126:127], v[76:77], off offset:512
	v_lshl_add_u64 v[76:77], v[118:119], 0, v[90:91]
	v_pk_mul_f32 v[76:77], v[78:79], v[74:75] op_sel_hi:[1,0]
	s_nop 0
	v_mov_b64_e32 v[80:81], v[146:147]
	v_mov_b64_e32 v[82:83], v[148:149]
	v_mov_b64_e32 v[114:115], v[162:163]
	v_mov_b64_e32 v[116:117], v[164:165]
	v_pk_add_f32 v[78:79], v[116:117], 1.0 op_sel_hi:[1,0]
	v_pk_add_f32 v[114:115], v[114:115], 1.0 op_sel_hi:[1,0]
	v_pk_fma_f32 v[76:77], v[78:79], v[76:77], v[82:83]
	v_pk_fma_f32 v[72:73], v[114:115], v[72:73], v[80:81]
	s_nop 0
	v_cvt_pk_bf16_f32 v72, v72, v73
	v_cvt_pk_bf16_f32 v73, v76, v77
	global_store_dwordx2 v[126:127], v[72:73], off offset:1024
	v_lshl_add_u64 v[72:73], v[118:119], 0, v[92:93]
	s_nop 0
	v_mov_b64_e32 v[76:77], v[150:151]
	v_mov_b64_e32 v[78:79], v[152:153]
	v_mov_b64_e32 v[80:81], v[166:167]
	v_mov_b64_e32 v[82:83], v[168:169]
	v_pk_add_f32 v[72:73], v[82:83], 1.0 op_sel_hi:[1,0]
	v_pk_add_f32 v[74:75], v[80:81], 1.0 op_sel_hi:[1,0]
	v_pk_fma_f32 v[70:71], v[72:73], v[70:71], v[78:79]
	v_pk_fma_f32 v[68:69], v[74:75], v[68:69], v[76:77]
	s_nop 0
	v_cvt_pk_bf16_f32 v68, v68, v69
	v_cvt_pk_bf16_f32 v69, v70, v71
	global_store_dwordx2 v[126:127], v[68:69], off offset:1536
	s_cbranch_vccnz .LBB0_123
	v_add_f32_e32 v68, v64, v65
	v_add_f32_e32 v69, v66, v67
	v_add_f32_e32 v68, v68, v69
	v_add_f32_e32 v69, v60, v61
	v_add_f32_e32 v70, v62, v63
	v_add_f32_e32 v68, 0, v68
	v_add_f32_e32 v69, v69, v70
	v_add_f32_e32 v68, v69, v68
	v_add_f32_e32 v69, v56, v57
	v_add_f32_e32 v70, v58, v59
	v_add_f32_e32 v69, v69, v70
	v_add_f32_e32 v68, v69, v68
	v_add_f32_e32 v69, v52, v53
	v_add_f32_e32 v70, v54, v55
	v_add_f32_e32 v69, v69, v70
	v_add_f32_e32 v68, v69, v68
	v_lshl_add_u64 v[78:79], v[16:17], 0, v[112:113]
	s_nop 0
	v_add_f32_dpp v68, v68, v68 row_ror:8 row_mask:0xf bank_mask:0xf bound_ctrl:1
	s_nop 1
	v_add_f32_dpp v68, v68, v68 row_ror:4 row_mask:0xf bank_mask:0xf bound_ctrl:1
	s_nop 1
	v_add_f32_dpp v68, v68, v68 row_ror:2 row_mask:0xf bank_mask:0xf bound_ctrl:1
	s_nop 1
	v_add_f32_dpp v68, v68, v68 row_ror:1 row_mask:0xf bank_mask:0xf bound_ctrl:1
	v_mov_b32_e32 v69, v68
	s_nop 1
	v_permlane16_swap_b32_e32 v68, v69
	v_add_f32_e32 v68, v68, v69
	v_mov_b32_e32 v69, v68
	s_nop 1
	v_permlane32_swap_b32_e32 v68, v69
	v_add_f32_e32 v68, v68, v69
	v_fmamk_f32 v67, v68, 0xba800000, v67
	v_fmac_f32_e32 v65, 0xba800000, v68
	v_fmamk_f32 v66, v68, 0xba800000, v66
	v_fmamk_f32 v64, v68, 0xba800000, v64
	v_mul_f32_e32 v69, v65, v65
	v_mul_f32_e32 v70, v67, v67
	v_fmac_f32_e32 v69, v64, v64
	v_fmac_f32_e32 v70, v66, v66
	v_fmamk_f32 v63, v68, 0xba800000, v63
	v_fmac_f32_e32 v61, 0xba800000, v68
	v_add_f32_e32 v69, v69, v70
	v_fmamk_f32 v62, v68, 0xba800000, v62
	v_fmamk_f32 v60, v68, 0xba800000, v60
	v_mul_f32_e32 v70, v61, v61
	v_mul_f32_e32 v71, v63, v63
	v_fmac_f32_e32 v70, v60, v60
	v_fmac_f32_e32 v71, v62, v62
	v_add_f32_e32 v70, v70, v71
	v_fmamk_f32 v59, v68, 0xba800000, v59
	v_fmac_f32_e32 v57, 0xba800000, v68
	v_add_f32_e32 v69, v69, v70
	v_fmamk_f32 v58, v68, 0xba800000, v58
	v_fmamk_f32 v56, v68, 0xba800000, v56
	v_mul_f32_e32 v70, v57, v57
	v_mul_f32_e32 v71, v59, v59
	v_fmac_f32_e32 v70, v56, v56
	v_fmac_f32_e32 v71, v58, v58
	v_add_f32_e32 v70, v70, v71
	v_fmamk_f32 v55, v68, 0xba800000, v55
	v_fmac_f32_e32 v53, 0xba800000, v68
	v_add_f32_e32 v69, v70, v69
	v_fmamk_f32 v54, v68, 0xba800000, v54
	v_fmamk_f32 v52, v68, 0xba800000, v52
	v_mul_f32_e32 v68, v53, v53
	v_mul_f32_e32 v70, v55, v55
	v_fmac_f32_e32 v68, v52, v52
	v_fmac_f32_e32 v70, v54, v54
	v_add_f32_e32 v68, v68, v70
	global_load_dwordx4 v[70:73], v[8:9], off
	global_load_dwordx4 v[74:77], v[12:13], off
	v_add_f32_e32 v68, v68, v69
	s_nop 1
	v_add_f32_dpp v68, v68, v68 row_ror:8 row_mask:0xf bank_mask:0xf bound_ctrl:1
	s_nop 1
	v_add_f32_dpp v68, v68, v68 row_ror:4 row_mask:0xf bank_mask:0xf bound_ctrl:1
	s_nop 1
	v_add_f32_dpp v68, v68, v68 row_ror:2 row_mask:0xf bank_mask:0xf bound_ctrl:1
	s_nop 1
	v_add_f32_dpp v68, v68, v68 row_ror:1 row_mask:0xf bank_mask:0xf bound_ctrl:1
	v_mov_b32_e32 v69, v68
	s_nop 1
	v_permlane16_swap_b32_e32 v68, v69
	v_add_f32_e32 v68, v68, v69
	v_mov_b32_e32 v69, v68
	s_nop 1
	v_permlane32_swap_b32_e32 v68, v69
	v_add_f32_e32 v68, v68, v69
	v_fmamk_f32 v68, v68, 0x3a800000, v196
	v_cmp_gt_f32_e32 vcc, s22, v68
	v_mul_f32_e32 v69, 0x4b800000, v68
	s_nop 0
	v_cndmask_b32_e32 v68, v68, v69, vcc
	v_rsq_f32_e32 v68, v68
	s_nop 0
	v_mul_f32_e32 v69, 0x45800000, v68
	v_cndmask_b32_e32 v68, v68, v69, vcc
	v_pk_mul_f32 v[64:65], v[64:65], v[68:69] op_sel_hi:[1,0]
	v_pk_mul_f32 v[66:67], v[66:67], v[68:69] op_sel_hi:[1,0]
	v_pk_mul_f32 v[62:63], v[62:63], v[68:69] op_sel_hi:[1,0]
	v_pk_mul_f32 v[60:61], v[60:61], v[68:69] op_sel_hi:[1,0]
	v_pk_mul_f32 v[58:59], v[58:59], v[68:69] op_sel_hi:[1,0]
	v_pk_mul_f32 v[56:57], v[56:57], v[68:69] op_sel_hi:[1,0]
	v_pk_mul_f32 v[54:55], v[54:55], v[68:69] op_sel_hi:[1,0]
	v_pk_mul_f32 v[52:53], v[52:53], v[68:69] op_sel_hi:[1,0]
	s_waitcnt vmcnt(0)
	v_pk_fma_f32 v[66:67], v[72:73], v[66:67], v[76:77]
	v_pk_fma_f32 v[64:65], v[70:71], v[64:65], v[74:75]
	global_store_dwordx4 v[78:79], v[64:67], off nt
	global_load_dwordx4 v[70:73], v[8:9], off offset:1024
	global_load_dwordx4 v[74:77], v[12:13], off offset:1024
	s_waitcnt vmcnt(0)
	v_pk_fma_f32 v[60:61], v[70:71], v[60:61], v[74:75]
	v_pk_fma_f32 v[62:63], v[72:73], v[62:63], v[76:77]
	global_store_dwordx4 v[78:79], v[60:63], off offset:1024 nt
	global_load_dwordx4 v[70:73], v[8:9], off offset:2048
	global_load_dwordx4 v[74:77], v[12:13], off offset:2048
	s_waitcnt vmcnt(0)
	v_pk_fma_f32 v[56:57], v[70:71], v[56:57], v[74:75]
	v_pk_fma_f32 v[58:59], v[72:73], v[58:59], v[76:77]
	global_store_dwordx4 v[78:79], v[56:59], off offset:2048 nt
	global_load_dwordx4 v[70:73], v[8:9], off offset:3072
	global_load_dwordx4 v[74:77], v[12:13], off offset:3072
	s_waitcnt vmcnt(0)
	v_pk_fma_f32 v[52:53], v[70:71], v[52:53], v[74:75]
	v_pk_fma_f32 v[54:55], v[72:73], v[54:55], v[76:77]
	global_store_dwordx4 v[78:79], v[52:55], off offset:3072 nt
.LBB0_123:
	v_add_f32_e32 v68, v64, v65
	v_add_f32_e32 v69, v66, v67
	v_add_f32_e32 v68, v68, v69
	v_add_f32_e32 v69, v60, v61
	v_add_f32_e32 v70, v62, v63
	v_add_f32_e32 v68, 0, v68
	v_add_f32_e32 v69, v69, v70
	v_add_f32_e32 v68, v69, v68
	v_add_f32_e32 v69, v56, v57
	v_add_f32_e32 v70, v58, v59
	v_add_f32_e32 v69, v69, v70
	v_add_f32_e32 v68, v69, v68
	v_add_f32_e32 v69, v52, v53
	v_add_f32_e32 v70, v54, v55
	v_add_f32_e32 v69, v69, v70
	v_add_f32_e32 v68, v69, v68
	v_lshrrev_b32_e32 v19, 20, v19
	v_add_u32_e32 v19, v110, v19
	v_add_f32_dpp v68, v68, v68 row_ror:8 row_mask:0xf bank_mask:0xf bound_ctrl:1
	v_ashrrev_i32_e32 v19, 12, v19
	v_add_u32_e32 v19, s2, v19
	v_add_f32_dpp v68, v68, v68 row_ror:4 row_mask:0xf bank_mask:0xf bound_ctrl:1
	s_nop 1
	v_add_f32_dpp v68, v68, v68 row_ror:2 row_mask:0xf bank_mask:0xf bound_ctrl:1
	s_nop 1
	v_add_f32_dpp v68, v68, v68 row_ror:1 row_mask:0xf bank_mask:0xf bound_ctrl:1
	v_mov_b32_e32 v69, v68
	s_nop 1
	v_permlane16_swap_b32_e32 v68, v69
	v_add_f32_e32 v68, v68, v69
	v_mov_b32_e32 v69, v68
	s_nop 1
	v_permlane32_swap_b32_e32 v68, v69
	v_add_f32_e32 v70, v68, v69
	v_fmamk_f32 v69, v70, 0xba800000, v67
	v_fmac_f32_e32 v65, 0xba800000, v70
	v_fmamk_f32 v68, v70, 0xba800000, v66
	v_fmamk_f32 v64, v70, 0xba800000, v64
	v_mul_f32_e32 v66, v65, v65
	v_mul_f32_e32 v67, v69, v69
	v_fmac_f32_e32 v66, v64, v64
	v_fmac_f32_e32 v67, v68, v68
	v_add_f32_e32 v71, v66, v67
	v_fmamk_f32 v67, v70, 0xba800000, v63
	v_fmac_f32_e32 v61, 0xba800000, v70
	v_fmamk_f32 v66, v70, 0xba800000, v62
	v_fmamk_f32 v60, v70, 0xba800000, v60
	v_mul_f32_e32 v62, v61, v61
	v_mul_f32_e32 v63, v67, v67
	v_fmac_f32_e32 v62, v60, v60
	v_fmac_f32_e32 v63, v66, v66
	v_add_f32_e32 v62, v62, v63
	v_fmamk_f32 v63, v70, 0xba800000, v59
	v_fmac_f32_e32 v57, 0xba800000, v70
	v_add_f32_e32 v71, v71, v62
	v_fmamk_f32 v62, v70, 0xba800000, v58
	v_fmamk_f32 v56, v70, 0xba800000, v56
	v_mul_f32_e32 v58, v57, v57
	v_mul_f32_e32 v59, v63, v63
	v_fmac_f32_e32 v58, v56, v56
	v_fmac_f32_e32 v59, v62, v62
	v_fmamk_f32 v55, v70, 0xba800000, v55
	v_fmac_f32_e32 v53, 0xba800000, v70
	v_add_f32_e32 v58, v58, v59
	v_fmamk_f32 v54, v70, 0xba800000, v54
	v_fmamk_f32 v52, v70, 0xba800000, v52
	v_mul_f32_e32 v59, v53, v53
	v_mul_f32_e32 v70, v55, v55
	v_fmac_f32_e32 v59, v52, v52
	v_fmac_f32_e32 v70, v54, v54
	v_add_f32_e32 v58, v58, v71
	v_add_f32_e32 v59, v59, v70
	v_mul_hi_i32_i24_e32 v71, 0x3000, v19
	v_mul_i32_i24_e32 v70, 0x3000, v19
	v_lshl_add_u64 v[72:73], s[84:85], 0, v[70:71]
	v_lshl_add_u64 v[70:71], v[72:73], 0, s[8:9]
	v_lshl_add_u64 v[72:73], v[72:73], 0, v[94:95]
	v_lshl_add_u64 v[78:79], v[70:71], 0, v[94:95]
	v_add_f32_e32 v58, v59, v58
	s_nop 0
	v_mov_b64_e32 v[74:75], v[138:139]
	v_mov_b64_e32 v[76:77], v[140:141]
	v_mov_b64_e32 v[78:79], v[154:155]
	v_mov_b64_e32 v[80:81], v[156:157]
	v_pk_add_f32 v[80:81], v[80:81], 1.0 op_sel_hi:[1,0]
	v_add_f32_dpp v58, v58, v58 row_ror:8 row_mask:0xf bank_mask:0xf bound_ctrl:1
	v_pk_add_f32 v[78:79], v[78:79], 1.0 op_sel_hi:[1,0]
	s_nop 0
	v_add_f32_dpp v58, v58, v58 row_ror:4 row_mask:0xf bank_mask:0xf bound_ctrl:1
	s_nop 1
	v_add_f32_dpp v58, v58, v58 row_ror:2 row_mask:0xf bank_mask:0xf bound_ctrl:1
	s_nop 1
	v_add_f32_dpp v58, v58, v58 row_ror:1 row_mask:0xf bank_mask:0xf bound_ctrl:1
	v_mov_b32_e32 v59, v58
	s_nop 1
	v_permlane16_swap_b32_e32 v58, v59
	v_add_f32_e32 v58, v58, v59
	v_mov_b32_e32 v59, v58
	s_nop 1
	v_permlane32_swap_b32_e32 v58, v59
	v_add_f32_e32 v58, v58, v59
	v_fmamk_f32 v58, v58, 0x3a800000, v196
	v_cmp_gt_f32_e32 vcc, s22, v58
	v_mul_f32_e32 v59, 0x4b800000, v58
	s_nop 0
	v_cndmask_b32_e32 v58, v58, v59, vcc
	v_rsq_f32_e32 v58, v58
	s_nop 0
	v_mul_f32_e32 v59, 0x45800000, v58
	v_cndmask_b32_e32 v58, v58, v59, vcc
	v_pk_mul_f32 v[64:65], v[64:65], v[58:59] op_sel_hi:[1,0]
	v_pk_mul_f32 v[68:69], v[68:69], v[58:59] op_sel_hi:[1,0]
	v_pk_fma_f32 v[64:65], v[78:79], v[64:65], v[74:75]
	v_pk_fma_f32 v[68:69], v[80:81], v[68:69], v[76:77]
	v_cvt_pk_bf16_f32 v64, v64, v65
	v_cvt_pk_bf16_f32 v65, v68, v69
	v_lshl_add_u64 v[68:69], v[84:85], 0, v[108:109]
	global_store_dwordx2 v[68:69], v[64:65], off
	v_lshl_add_u64 v[64:65], v[70:71], 0, v[88:89]
	v_pk_mul_f32 v[60:61], v[60:61], v[58:59] op_sel_hi:[1,0]
	v_pk_mul_f32 v[64:65], v[66:67], v[58:59] op_sel_hi:[1,0]
	v_pk_mul_f32 v[56:57], v[56:57], v[58:59] op_sel_hi:[1,0]
	v_pk_mul_f32 v[52:53], v[52:53], v[58:59] op_sel_hi:[1,0]
	v_pk_mul_f32 v[54:55], v[54:55], v[58:59] op_sel_hi:[1,0]
	s_and_b64 vcc, exec, s[38:39]
	s_nop 0
	v_mov_b64_e32 v[74:75], v[142:143]
	v_mov_b64_e32 v[76:77], v[144:145]
	v_mov_b64_e32 v[78:79], v[158:159]
	v_mov_b64_e32 v[80:81], v[160:161]
	v_pk_add_f32 v[66:67], v[80:81], 1.0 op_sel_hi:[1,0]
	v_pk_add_f32 v[78:79], v[78:79], 1.0 op_sel_hi:[1,0]
	v_pk_fma_f32 v[64:65], v[66:67], v[64:65], v[76:77]
	v_pk_fma_f32 v[60:61], v[78:79], v[60:61], v[74:75]
	s_nop 0
	v_cvt_pk_bf16_f32 v60, v60, v61
	v_cvt_pk_bf16_f32 v61, v64, v65
	global_store_dwordx2 v[68:69], v[60:61], off offset:512
	v_lshl_add_u64 v[60:61], v[70:71], 0, v[90:91]
	v_pk_mul_f32 v[60:61], v[62:63], v[58:59] op_sel_hi:[1,0]
	s_nop 0
	v_mov_b64_e32 v[64:65], v[146:147]
	v_mov_b64_e32 v[66:67], v[148:149]
	v_mov_b64_e32 v[74:75], v[162:163]
	v_mov_b64_e32 v[76:77], v[164:165]
	v_pk_add_f32 v[62:63], v[76:77], 1.0 op_sel_hi:[1,0]
	v_pk_add_f32 v[74:75], v[74:75], 1.0 op_sel_hi:[1,0]
	v_pk_fma_f32 v[60:61], v[62:63], v[60:61], v[66:67]
	v_pk_fma_f32 v[56:57], v[74:75], v[56:57], v[64:65]
	s_nop 0
	v_cvt_pk_bf16_f32 v56, v56, v57
	v_cvt_pk_bf16_f32 v57, v60, v61
	global_store_dwordx2 v[68:69], v[56:57], off offset:1024
	v_lshl_add_u64 v[56:57], v[70:71], 0, v[92:93]
	s_nop 0
	v_mov_b64_e32 v[60:61], v[150:151]
	v_mov_b64_e32 v[62:63], v[152:153]
	v_mov_b64_e32 v[64:65], v[166:167]
	v_mov_b64_e32 v[66:67], v[168:169]
	v_pk_add_f32 v[56:57], v[66:67], 1.0 op_sel_hi:[1,0]
	v_pk_add_f32 v[58:59], v[64:65], 1.0 op_sel_hi:[1,0]
	v_pk_fma_f32 v[54:55], v[56:57], v[54:55], v[62:63]
	v_pk_fma_f32 v[52:53], v[58:59], v[52:53], v[60:61]
	s_nop 0
	v_cvt_pk_bf16_f32 v52, v52, v53
	v_cvt_pk_bf16_f32 v53, v54, v55
	global_store_dwordx2 v[68:69], v[52:53], off offset:1536
	s_cbranch_vccnz .LBB0_125
	v_add_f32_e32 v19, v48, v49
	v_add_f32_e32 v52, v50, v51
	v_add_f32_e32 v19, v19, v52
	v_add_f32_e32 v52, v44, v45
	v_add_f32_e32 v53, v46, v47
	v_add_f32_e32 v19, 0, v19
	v_add_f32_e32 v52, v52, v53
	v_add_f32_e32 v19, v52, v19
	v_add_f32_e32 v52, v40, v41
	v_add_f32_e32 v53, v42, v43
	v_add_f32_e32 v52, v52, v53
	v_add_f32_e32 v19, v52, v19
	v_add_f32_e32 v52, v36, v37
	v_add_f32_e32 v53, v38, v39
	v_add_f32_e32 v52, v52, v53
	v_add_f32_e32 v19, v52, v19
	v_lshl_add_u64 v[62:63], v[16:17], 0, v[106:107]
	s_nop 0
	v_add_f32_dpp v19, v19, v19 row_ror:8 row_mask:0xf bank_mask:0xf bound_ctrl:1
	s_nop 1
	v_add_f32_dpp v19, v19, v19 row_ror:4 row_mask:0xf bank_mask:0xf bound_ctrl:1
	s_nop 1
	v_add_f32_dpp v19, v19, v19 row_ror:2 row_mask:0xf bank_mask:0xf bound_ctrl:1
	s_nop 1
	v_add_f32_dpp v19, v19, v19 row_ror:1 row_mask:0xf bank_mask:0xf bound_ctrl:1
	v_mov_b32_e32 v52, v19
	s_nop 1
	v_permlane16_swap_b32_e32 v19, v52
	v_add_f32_e32 v19, v19, v52
	v_mov_b32_e32 v52, v19
	s_nop 1
	v_permlane32_swap_b32_e32 v19, v52
	v_add_f32_e32 v19, v19, v52
	v_fmamk_f32 v51, v19, 0xba800000, v51
	v_fmac_f32_e32 v49, 0xba800000, v19
	v_fmamk_f32 v50, v19, 0xba800000, v50
	v_fmamk_f32 v48, v19, 0xba800000, v48
	v_mul_f32_e32 v52, v49, v49
	v_mul_f32_e32 v53, v51, v51
	v_fmac_f32_e32 v52, v48, v48
	v_fmac_f32_e32 v53, v50, v50
	v_fmamk_f32 v47, v19, 0xba800000, v47
	v_fmac_f32_e32 v45, 0xba800000, v19
	v_add_f32_e32 v52, v52, v53
	v_fmamk_f32 v46, v19, 0xba800000, v46
	v_fmamk_f32 v44, v19, 0xba800000, v44
	v_mul_f32_e32 v53, v45, v45
	v_mul_f32_e32 v54, v47, v47
	v_fmac_f32_e32 v53, v44, v44
	v_fmac_f32_e32 v54, v46, v46
	v_add_f32_e32 v53, v53, v54
	v_fmamk_f32 v43, v19, 0xba800000, v43
	v_fmac_f32_e32 v41, 0xba800000, v19
	v_add_f32_e32 v52, v52, v53
	v_fmamk_f32 v42, v19, 0xba800000, v42
	v_fmamk_f32 v40, v19, 0xba800000, v40
	v_mul_f32_e32 v53, v41, v41
	v_mul_f32_e32 v54, v43, v43
	v_fmac_f32_e32 v53, v40, v40
	v_fmac_f32_e32 v54, v42, v42
	v_add_f32_e32 v53, v53, v54
	global_load_dwordx4 v[54:57], v[8:9], off
	global_load_dwordx4 v[58:61], v[12:13], off
	v_fmamk_f32 v39, v19, 0xba800000, v39
	v_fmac_f32_e32 v37, 0xba800000, v19
	v_add_f32_e32 v52, v53, v52
	v_fmamk_f32 v38, v19, 0xba800000, v38
	v_fmamk_f32 v36, v19, 0xba800000, v36
	v_mul_f32_e32 v19, v37, v37
	v_mul_f32_e32 v53, v39, v39
	v_fmac_f32_e32 v19, v36, v36
	v_fmac_f32_e32 v53, v38, v38
	v_add_f32_e32 v19, v19, v53
	v_add_f32_e32 v19, v19, v52
	s_nop 1
	v_add_f32_dpp v19, v19, v19 row_ror:8 row_mask:0xf bank_mask:0xf bound_ctrl:1
	s_nop 1
	v_add_f32_dpp v19, v19, v19 row_ror:4 row_mask:0xf bank_mask:0xf bound_ctrl:1
	s_nop 1
	v_add_f32_dpp v19, v19, v19 row_ror:2 row_mask:0xf bank_mask:0xf bound_ctrl:1
	s_nop 1
	v_add_f32_dpp v19, v19, v19 row_ror:1 row_mask:0xf bank_mask:0xf bound_ctrl:1
	v_mov_b32_e32 v52, v19
	s_nop 1
	v_permlane16_swap_b32_e32 v19, v52
	v_add_f32_e32 v19, v19, v52
	v_mov_b32_e32 v52, v19
	s_nop 1
	v_permlane32_swap_b32_e32 v19, v52
	v_add_f32_e32 v19, v19, v52
	v_fmamk_f32 v19, v19, 0x3a800000, v196
	v_cmp_gt_f32_e32 vcc, s22, v19
	v_mul_f32_e32 v52, 0x4b800000, v19
	s_nop 0
	v_cndmask_b32_e32 v19, v19, v52, vcc
	v_rsq_f32_e32 v19, v19
	s_nop 0
	v_mul_f32_e32 v52, 0x45800000, v19
	v_cndmask_b32_e32 v52, v19, v52, vcc
	v_pk_mul_f32 v[48:49], v[48:49], v[52:53] op_sel_hi:[1,0]
	v_pk_mul_f32 v[50:51], v[50:51], v[52:53] op_sel_hi:[1,0]
	v_pk_mul_f32 v[46:47], v[46:47], v[52:53] op_sel_hi:[1,0]
	v_pk_mul_f32 v[44:45], v[44:45], v[52:53] op_sel_hi:[1,0]
	v_pk_mul_f32 v[42:43], v[42:43], v[52:53] op_sel_hi:[1,0]
	v_pk_mul_f32 v[40:41], v[40:41], v[52:53] op_sel_hi:[1,0]
	v_pk_mul_f32 v[38:39], v[38:39], v[52:53] op_sel_hi:[1,0]
	v_pk_mul_f32 v[36:37], v[36:37], v[52:53] op_sel_hi:[1,0]
	s_waitcnt vmcnt(0)
	v_pk_fma_f32 v[50:51], v[56:57], v[50:51], v[60:61]
	v_pk_fma_f32 v[48:49], v[54:55], v[48:49], v[58:59]
	global_store_dwordx4 v[62:63], v[48:51], off nt
	global_load_dwordx4 v[54:57], v[8:9], off offset:1024
	global_load_dwordx4 v[58:61], v[12:13], off offset:1024
	s_waitcnt vmcnt(0)
	v_pk_fma_f32 v[44:45], v[54:55], v[44:45], v[58:59]
	v_pk_fma_f32 v[46:47], v[56:57], v[46:47], v[60:61]
	global_store_dwordx4 v[62:63], v[44:47], off offset:1024 nt
	global_load_dwordx4 v[54:57], v[8:9], off offset:2048
	global_load_dwordx4 v[58:61], v[12:13], off offset:2048
	s_waitcnt vmcnt(0)
	v_pk_fma_f32 v[40:41], v[54:55], v[40:41], v[58:59]
	v_pk_fma_f32 v[42:43], v[56:57], v[42:43], v[60:61]
	global_store_dwordx4 v[62:63], v[40:43], off offset:2048 nt
	global_load_dwordx4 v[54:57], v[8:9], off offset:3072
	global_load_dwordx4 v[58:61], v[12:13], off offset:3072
	s_waitcnt vmcnt(0)
	v_pk_fma_f32 v[36:37], v[54:55], v[36:37], v[58:59]
	v_pk_fma_f32 v[38:39], v[56:57], v[38:39], v[60:61]
	global_store_dwordx4 v[62:63], v[36:39], off offset:3072 nt
.LBB0_125:
	v_add_f32_e32 v19, v48, v49
	v_add_f32_e32 v52, v50, v51
	v_add_f32_e32 v19, v19, v52
	v_add_f32_e32 v52, v44, v45
	v_add_f32_e32 v53, v46, v47
	v_add_f32_e32 v19, 0, v19
	v_add_f32_e32 v52, v52, v53
	v_add_f32_e32 v19, v52, v19
	v_add_f32_e32 v52, v40, v41
	v_add_f32_e32 v53, v42, v43
	v_add_f32_e32 v52, v52, v53
	v_add_f32_e32 v19, v52, v19
	v_add_f32_e32 v52, v36, v37
	v_add_f32_e32 v53, v38, v39
	v_add_f32_e32 v52, v52, v53
	v_add_f32_e32 v19, v52, v19
	v_lshrrev_b32_e32 v15, 20, v15
	v_add_u32_e32 v15, v104, v15
	v_add_f32_dpp v19, v19, v19 row_ror:8 row_mask:0xf bank_mask:0xf bound_ctrl:1
	v_ashrrev_i32_e32 v15, 12, v15
	v_add_u32_e32 v15, s2, v15
	v_add_f32_dpp v19, v19, v19 row_ror:4 row_mask:0xf bank_mask:0xf bound_ctrl:1
	v_mul_hi_i32_i24_e32 v55, 0x3000, v15
	v_mov_b32_e32 v95, v2
	v_add_f32_dpp v19, v19, v19 row_ror:2 row_mask:0xf bank_mask:0xf bound_ctrl:1
	v_mov_b32_e32 v89, v2
	v_mov_b32_e32 v91, v2
	v_add_f32_dpp v19, v19, v19 row_ror:1 row_mask:0xf bank_mask:0xf bound_ctrl:1
	v_mov_b32_e32 v52, v19
	s_nop 1
	v_permlane16_swap_b32_e32 v19, v52
	v_add_f32_e32 v19, v19, v52
	v_mov_b32_e32 v52, v19
	s_nop 1
	v_permlane32_swap_b32_e32 v19, v52
	v_add_f32_e32 v19, v19, v52
	v_fmamk_f32 v53, v19, 0xba800000, v51
	v_fmac_f32_e32 v49, 0xba800000, v19
	v_fmamk_f32 v52, v19, 0xba800000, v50
	v_fmamk_f32 v48, v19, 0xba800000, v48
	v_mul_f32_e32 v50, v49, v49
	v_mul_f32_e32 v51, v53, v53
	v_fmac_f32_e32 v50, v48, v48
	v_fmac_f32_e32 v51, v52, v52
	v_add_f32_e32 v54, v50, v51
	v_fmamk_f32 v51, v19, 0xba800000, v47
	v_fmac_f32_e32 v45, 0xba800000, v19
	v_fmamk_f32 v50, v19, 0xba800000, v46
	v_fmamk_f32 v44, v19, 0xba800000, v44
	v_mul_f32_e32 v46, v45, v45
	v_mul_f32_e32 v47, v51, v51
	v_fmac_f32_e32 v46, v44, v44
	v_fmac_f32_e32 v47, v50, v50
	v_add_f32_e32 v46, v46, v47
	v_fmamk_f32 v47, v19, 0xba800000, v43
	v_fmac_f32_e32 v41, 0xba800000, v19
	v_add_f32_e32 v54, v54, v46
	v_fmamk_f32 v46, v19, 0xba800000, v42
	v_fmamk_f32 v40, v19, 0xba800000, v40
	v_mul_f32_e32 v42, v41, v41
	v_mul_f32_e32 v43, v47, v47
	v_fmac_f32_e32 v42, v40, v40
	v_fmac_f32_e32 v43, v46, v46
	v_add_f32_e32 v42, v42, v43
	v_add_f32_e32 v42, v42, v54
	v_mul_i32_i24_e32 v54, 0x3000, v15
	v_lshl_add_u64 v[56:57], s[84:85], 0, v[54:55]
	v_lshl_add_u64 v[54:55], v[56:57], 0, s[8:9]
	v_lshl_add_u64 v[56:57], v[56:57], 0, v[94:95]
	v_lshl_add_u64 v[62:63], v[54:55], 0, v[94:95]
	v_fmamk_f32 v39, v19, 0xba800000, v39
	v_fmac_f32_e32 v37, 0xba800000, v19
	v_fmamk_f32 v38, v19, 0xba800000, v38
	v_fmamk_f32 v36, v19, 0xba800000, v36
	v_mul_f32_e32 v19, v37, v37
	v_mul_f32_e32 v43, v39, v39
	v_fmac_f32_e32 v19, v36, v36
	v_fmac_f32_e32 v43, v38, v38
	v_add_f32_e32 v19, v19, v43
	v_add_f32_e32 v19, v19, v42
	v_mov_b32_e32 v93, v2
	s_nop 0
	v_mov_b64_e32 v[58:59], v[138:139]
	v_mov_b64_e32 v[60:61], v[140:141]
	v_mov_b64_e32 v[62:63], v[154:155]
	v_mov_b64_e32 v[64:65], v[156:157]
	v_pk_add_f32 v[64:65], v[64:65], 1.0 op_sel_hi:[1,0]
	v_add_f32_dpp v19, v19, v19 row_ror:8 row_mask:0xf bank_mask:0xf bound_ctrl:1
	v_pk_add_f32 v[62:63], v[62:63], 1.0 op_sel_hi:[1,0]
	s_nop 0
	v_add_f32_dpp v19, v19, v19 row_ror:4 row_mask:0xf bank_mask:0xf bound_ctrl:1
	s_nop 1
	v_add_f32_dpp v19, v19, v19 row_ror:2 row_mask:0xf bank_mask:0xf bound_ctrl:1
	s_nop 1
	v_add_f32_dpp v19, v19, v19 row_ror:1 row_mask:0xf bank_mask:0xf bound_ctrl:1
	v_mov_b32_e32 v42, v19
	s_nop 1
	v_permlane16_swap_b32_e32 v19, v42
	v_add_f32_e32 v19, v19, v42
	v_mov_b32_e32 v42, v19
	s_nop 1
	v_permlane32_swap_b32_e32 v19, v42
	v_add_f32_e32 v19, v19, v42
	v_fmamk_f32 v19, v19, 0x3a800000, v196
	v_cmp_gt_f32_e32 vcc, s22, v19
	v_mul_f32_e32 v42, 0x4b800000, v19
	s_nop 0
	v_cndmask_b32_e32 v19, v19, v42, vcc
	v_rsq_f32_e32 v19, v19
	s_nop 0
	v_mul_f32_e32 v42, 0x45800000, v19
	v_cndmask_b32_e32 v42, v19, v42, vcc
	v_pk_mul_f32 v[48:49], v[48:49], v[42:43] op_sel_hi:[1,0]
	v_pk_mul_f32 v[52:53], v[52:53], v[42:43] op_sel_hi:[1,0]
	v_pk_fma_f32 v[48:49], v[62:63], v[48:49], v[58:59]
	v_pk_fma_f32 v[52:53], v[64:65], v[52:53], v[60:61]
	v_cvt_pk_bf16_f32 v48, v48, v49
	v_cvt_pk_bf16_f32 v49, v52, v53
	v_lshl_add_u64 v[52:53], v[84:85], 0, v[102:103]
	global_store_dwordx2 v[52:53], v[48:49], off
	v_lshl_add_u64 v[48:49], v[54:55], 0, v[88:89]
	v_pk_mul_f32 v[44:45], v[44:45], v[42:43] op_sel_hi:[1,0]
	v_pk_mul_f32 v[48:49], v[50:51], v[42:43] op_sel_hi:[1,0]
	v_pk_mul_f32 v[40:41], v[40:41], v[42:43] op_sel_hi:[1,0]
	v_pk_mul_f32 v[36:37], v[36:37], v[42:43] op_sel_hi:[1,0]
	v_pk_mul_f32 v[38:39], v[38:39], v[42:43] op_sel_hi:[1,0]
	s_and_b64 vcc, exec, s[38:39]
	s_nop 0
	v_mov_b64_e32 v[58:59], v[142:143]
	v_mov_b64_e32 v[60:61], v[144:145]
	v_mov_b64_e32 v[62:63], v[158:159]
	v_mov_b64_e32 v[64:65], v[160:161]
	v_pk_add_f32 v[50:51], v[64:65], 1.0 op_sel_hi:[1,0]
	v_pk_add_f32 v[62:63], v[62:63], 1.0 op_sel_hi:[1,0]
	v_pk_fma_f32 v[48:49], v[50:51], v[48:49], v[60:61]
	v_pk_fma_f32 v[44:45], v[62:63], v[44:45], v[58:59]
	s_nop 0
	v_cvt_pk_bf16_f32 v44, v44, v45
	v_cvt_pk_bf16_f32 v45, v48, v49
	global_store_dwordx2 v[52:53], v[44:45], off offset:512
	v_lshl_add_u64 v[44:45], v[54:55], 0, v[90:91]
	v_pk_mul_f32 v[44:45], v[46:47], v[42:43] op_sel_hi:[1,0]
	s_nop 0
	v_mov_b64_e32 v[48:49], v[146:147]
	v_mov_b64_e32 v[50:51], v[148:149]
	v_mov_b64_e32 v[58:59], v[162:163]
	v_mov_b64_e32 v[60:61], v[164:165]
	v_pk_add_f32 v[46:47], v[60:61], 1.0 op_sel_hi:[1,0]
	v_pk_add_f32 v[58:59], v[58:59], 1.0 op_sel_hi:[1,0]
	v_pk_fma_f32 v[44:45], v[46:47], v[44:45], v[50:51]
	v_pk_fma_f32 v[40:41], v[58:59], v[40:41], v[48:49]
	s_nop 0
	v_cvt_pk_bf16_f32 v40, v40, v41
	v_cvt_pk_bf16_f32 v41, v44, v45
	global_store_dwordx2 v[52:53], v[40:41], off offset:1024
	v_lshl_add_u64 v[40:41], v[54:55], 0, v[92:93]
	s_nop 0
	v_mov_b64_e32 v[44:45], v[150:151]
	v_mov_b64_e32 v[46:47], v[152:153]
	v_mov_b64_e32 v[48:49], v[166:167]
	v_mov_b64_e32 v[50:51], v[168:169]
	v_pk_add_f32 v[40:41], v[50:51], 1.0 op_sel_hi:[1,0]
	v_pk_add_f32 v[42:43], v[48:49], 1.0 op_sel_hi:[1,0]
	v_pk_fma_f32 v[38:39], v[40:41], v[38:39], v[46:47]
	v_pk_fma_f32 v[36:37], v[42:43], v[36:37], v[44:45]
	s_nop 0
	v_cvt_pk_bf16_f32 v36, v36, v37
	v_cvt_pk_bf16_f32 v37, v38, v39
	global_store_dwordx2 v[52:53], v[36:37], off offset:1536
	s_cbranch_vccnz .LBB0_110
	global_load_dwordx4 v[38:41], v[8:9], off
	global_load_dwordx4 v[42:45], v[12:13], off
	v_add_f32_e32 v15, v32, v33
	v_add_f32_e32 v19, v34, v35
	v_add_f32_e32 v15, v15, v19
	v_add_f32_e32 v19, v28, v29
	v_add_f32_e32 v36, v30, v31
	v_add_f32_e32 v15, 0, v15
	v_add_f32_e32 v19, v19, v36
	v_add_f32_e32 v15, v19, v15
	v_add_f32_e32 v19, v24, v25
	v_add_f32_e32 v36, v26, v27
	v_add_f32_e32 v19, v19, v36
	v_add_f32_e32 v15, v19, v15
	v_add_f32_e32 v19, v20, v21
	v_add_f32_e32 v36, v22, v23
	v_add_f32_e32 v19, v19, v36
	v_add_f32_e32 v15, v19, v15
	v_lshl_add_u64 v[46:47], v[16:17], 0, v[100:101]
	s_nop 0
	v_add_f32_dpp v15, v15, v15 row_ror:8 row_mask:0xf bank_mask:0xf bound_ctrl:1
	s_nop 1
	v_add_f32_dpp v15, v15, v15 row_ror:4 row_mask:0xf bank_mask:0xf bound_ctrl:1
	s_nop 1
	v_add_f32_dpp v15, v15, v15 row_ror:2 row_mask:0xf bank_mask:0xf bound_ctrl:1
	s_nop 1
	v_add_f32_dpp v15, v15, v15 row_ror:1 row_mask:0xf bank_mask:0xf bound_ctrl:1
	v_mov_b32_e32 v19, v15
	s_nop 1
	v_permlane16_swap_b32_e32 v15, v19
	v_add_f32_e32 v15, v15, v19
	v_mov_b32_e32 v19, v15
	s_nop 1
	v_permlane32_swap_b32_e32 v15, v19
	v_add_f32_e32 v15, v15, v19
	v_fmamk_f32 v35, v15, 0xba800000, v35
	v_fmac_f32_e32 v33, 0xba800000, v15
	v_fmamk_f32 v34, v15, 0xba800000, v34
	v_fmamk_f32 v32, v15, 0xba800000, v32
	v_mul_f32_e32 v19, v33, v33
	v_mul_f32_e32 v36, v35, v35
	v_fmac_f32_e32 v19, v32, v32
	v_fmac_f32_e32 v36, v34, v34
	v_fmamk_f32 v31, v15, 0xba800000, v31
	v_fmac_f32_e32 v29, 0xba800000, v15
	v_add_f32_e32 v19, v19, v36
	v_fmamk_f32 v30, v15, 0xba800000, v30
	v_fmamk_f32 v28, v15, 0xba800000, v28
	v_mul_f32_e32 v36, v29, v29
	v_mul_f32_e32 v37, v31, v31
	v_fmac_f32_e32 v36, v28, v28
	v_fmac_f32_e32 v37, v30, v30
	v_add_f32_e32 v36, v36, v37
	v_fmamk_f32 v27, v15, 0xba800000, v27
	v_fmac_f32_e32 v25, 0xba800000, v15
	v_add_f32_e32 v19, v19, v36
	v_fmamk_f32 v26, v15, 0xba800000, v26
	v_fmamk_f32 v24, v15, 0xba800000, v24
	v_mul_f32_e32 v36, v25, v25
	v_mul_f32_e32 v37, v27, v27
	v_fmac_f32_e32 v36, v24, v24
	v_fmac_f32_e32 v37, v26, v26
	v_add_f32_e32 v36, v36, v37
	v_fmamk_f32 v23, v15, 0xba800000, v23
	v_fmac_f32_e32 v21, 0xba800000, v15
	v_add_f32_e32 v19, v36, v19
	v_fmamk_f32 v22, v15, 0xba800000, v22
	v_fmamk_f32 v20, v15, 0xba800000, v20
	v_mul_f32_e32 v15, v21, v21
	v_mul_f32_e32 v36, v23, v23
	v_fmac_f32_e32 v15, v20, v20
	v_fmac_f32_e32 v36, v22, v22
	v_add_f32_e32 v15, v15, v36
	v_add_f32_e32 v15, v15, v19
	s_nop 1
	v_add_f32_dpp v15, v15, v15 row_ror:8 row_mask:0xf bank_mask:0xf bound_ctrl:1
	s_nop 1
	v_add_f32_dpp v15, v15, v15 row_ror:4 row_mask:0xf bank_mask:0xf bound_ctrl:1
	s_nop 1
	v_add_f32_dpp v15, v15, v15 row_ror:2 row_mask:0xf bank_mask:0xf bound_ctrl:1
	s_nop 1
	v_add_f32_dpp v15, v15, v15 row_ror:1 row_mask:0xf bank_mask:0xf bound_ctrl:1
	v_mov_b32_e32 v19, v15
	s_nop 1
	v_permlane16_swap_b32_e32 v15, v19
	v_add_f32_e32 v15, v15, v19
	v_mov_b32_e32 v19, v15
	s_nop 1
	v_permlane32_swap_b32_e32 v15, v19
	v_add_f32_e32 v15, v15, v19
	v_fmamk_f32 v15, v15, 0x3a800000, v196
	v_cmp_gt_f32_e32 vcc, s22, v15
	v_mul_f32_e32 v19, 0x4b800000, v15
	s_nop 0
	v_cndmask_b32_e32 v15, v15, v19, vcc
	v_rsq_f32_e32 v15, v15
	s_nop 0
	v_mul_f32_e32 v19, 0x45800000, v15
	v_cndmask_b32_e32 v36, v15, v19, vcc
	v_pk_mul_f32 v[32:33], v[32:33], v[36:37] op_sel_hi:[1,0]
	v_pk_mul_f32 v[34:35], v[34:35], v[36:37] op_sel_hi:[1,0]
	s_waitcnt vmcnt(0)
	v_pk_fma_f32 v[32:33], v[38:39], v[32:33], v[42:43]
	v_pk_fma_f32 v[34:35], v[40:41], v[34:35], v[44:45]
	global_store_dwordx4 v[46:47], v[32:35], off nt
	global_load_dwordx4 v[38:41], v[8:9], off offset:1024
	global_load_dwordx4 v[42:45], v[12:13], off offset:1024
	v_pk_mul_f32 v[30:31], v[30:31], v[36:37] op_sel_hi:[1,0]
	v_pk_mul_f32 v[28:29], v[28:29], v[36:37] op_sel_hi:[1,0]
	v_pk_mul_f32 v[26:27], v[26:27], v[36:37] op_sel_hi:[1,0]
	v_pk_mul_f32 v[24:25], v[24:25], v[36:37] op_sel_hi:[1,0]
	v_pk_mul_f32 v[22:23], v[22:23], v[36:37] op_sel_hi:[1,0]
	v_pk_mul_f32 v[20:21], v[20:21], v[36:37] op_sel_hi:[1,0]
	s_waitcnt vmcnt(0)
	v_pk_fma_f32 v[28:29], v[38:39], v[28:29], v[42:43]
	v_pk_fma_f32 v[30:31], v[40:41], v[30:31], v[44:45]
	global_store_dwordx4 v[46:47], v[28:31], off offset:1024 nt
	global_load_dwordx4 v[38:41], v[8:9], off offset:2048
	global_load_dwordx4 v[42:45], v[12:13], off offset:2048
	s_waitcnt vmcnt(0)
	v_pk_fma_f32 v[24:25], v[38:39], v[24:25], v[42:43]
	v_pk_fma_f32 v[26:27], v[40:41], v[26:27], v[44:45]
	global_store_dwordx4 v[46:47], v[24:27], off offset:2048 nt
	global_load_dwordx4 v[38:41], v[8:9], off offset:3072
	global_load_dwordx4 v[42:45], v[12:13], off offset:3072
	s_waitcnt vmcnt(0)
	v_pk_fma_f32 v[20:21], v[38:39], v[20:21], v[42:43]
	v_pk_fma_f32 v[22:23], v[40:41], v[22:23], v[44:45]
	global_store_dwordx4 v[46:47], v[20:23], off offset:3072 nt
	s_branch .LBB0_110
